# GU GEMM epilogue rewritten by hand with packed f32 math (about half the instructions, same per-element operation order)
# speedup vs baseline: 1.0129x; 1.0104x over previous
; __device__ __forceinline__ unsigned pk2(float lo, float hi) { unsigned r; asm("v_cvt_pk_bf16_f32 %0, %1, %2" : "=v"(r) : "v"(lo), "v"(hi)); return r; }
; __device__ __forceinline__ float silu_f(float x) { return x * sigmoid_f(x); }
;     __device__ __forceinline__ void operator()(const f32x4 (&acc)[2][2][4][2], const pg8::Unit& u, int wr, int wc, int fr, int fq) const {
;     ...
;             for (int m = 0; m < 4; ++m) rs[ai][m] = ss[row0 + ai * 128 + m * 16];
; #pragma unroll
;         for (int ai = 0; ai < 2; ++ai)
; #pragma unroll
;             for (int m = 0; m < 4; ++m) {
;                 const int r = row0 + ai * 128 + m * 16;
;                 const float rstd = __builtin_amdgcn_rsqf(rs[ai][m] * (1.0f / D) + EPS);
;                 float o[8];
; #pragma unroll
;                 for (int n = 0; n < 2; ++n)
; #pragma unroll
;                     for (int e = 0; e < 4; ++e) { const float g = acc[ai][0][m][n][e] * rstd, up = acc[ai][1][m][n][e] * rstd; o[4 * n + e] = silu_f(g) * up; }
;                 u32x4 w; w.x = pk2(o[0], o[1]); w.y = pk2(o[2], o[3]); w.z = pk2(o[4], o[5]); w.w = pk2(o[6], o[7]);
;                 *(u32x4*)(ACT + (size_t)r * FF + col0) = w;
.LBB0_526:
	s_lshl_b32 s2, s45, 8
	s_add_i32 s2, s2, s39
	v_add_u32_e32 v140, s2, v145
	v_lshlrev_b32_e32 v141, 2, v140
	global_load_dword v150, v141, s[12:13]
	global_load_dword v152, v141, s[12:13] offset:64
	global_load_dword v154, v141, s[12:13] offset:128
	global_load_dword v156, v141, s[12:13] offset:192
	global_load_dword v158, v141, s[12:13] offset:512
	global_load_dword v160, v141, s[12:13] offset:576
	global_load_dword v144, v141, s[12:13] offset:640
	global_load_dword v174, v141, s[12:13] offset:704
	s_lshl_b32 s2, s44, 7
	s_or_b32 s2, s2, s40
	v_lshl_add_u32 v142, v146, 3, s2
	s_movk_i32 s17, 0x1600
	v_mul_lo_u32 v171, v140, s17
	v_lshl_add_u32 v171, v142, 1, v171
	s_mov_b32 s2, 0xbfb8aa3b
	s_waitcnt vmcnt(0)
	v_fmamk_f32 v150, v150, 0x3a800000, v199
	v_fmamk_f32 v152, v152, 0x3a800000, v199
	v_fmamk_f32 v154, v154, 0x3a800000, v199
	v_fmamk_f32 v156, v156, 0x3a800000, v199
	v_fmamk_f32 v158, v158, 0x3a800000, v199
	v_fmamk_f32 v160, v160, 0x3a800000, v199
	v_fmamk_f32 v144, v144, 0x3a800000, v199
	v_fmamk_f32 v174, v174, 0x3a800000, v199
	v_rsq_f32_e32 v150, v150
	v_rsq_f32_e32 v152, v152
	v_rsq_f32_e32 v154, v154
	v_rsq_f32_e32 v156, v156
	v_rsq_f32_e32 v158, v158
	v_rsq_f32_e32 v160, v160
	v_rsq_f32_e32 v144, v144
	v_rsq_f32_e32 v174, v174
	v_pk_mul_f32 v[124:125], v[124:125], v[150:151] op_sel_hi:[1,0]
	v_pk_mul_f32 v[120:121], v[120:121], v[150:151] op_sel_hi:[1,0]
	v_pk_mul_f32 v[126:127], v[126:127], v[150:151] op_sel_hi:[1,0]
	v_pk_mul_f32 v[122:123], v[122:123], v[150:151] op_sel_hi:[1,0]
	v_pk_mul_f32 v[140:141], v[124:125], s[2:3] op_sel_hi:[1,0]
	v_pk_mul_f32 v[142:143], v[126:127], s[2:3] op_sel_hi:[1,0]
	v_exp_f32_e32 v140, v140
	v_exp_f32_e32 v141, v141
	v_exp_f32_e32 v142, v142
	v_exp_f32_e32 v143, v143
	v_pk_add_f32 v[140:141], v[140:141], 1.0 op_sel_hi:[1,0]
	v_pk_add_f32 v[142:143], v[142:143], 1.0 op_sel_hi:[1,0]
	v_rcp_f32_e32 v140, v140
	v_rcp_f32_e32 v141, v141
	v_rcp_f32_e32 v142, v142
	v_rcp_f32_e32 v143, v143
	v_pk_mul_f32 v[124:125], v[124:125], v[140:141]
	v_pk_mul_f32 v[126:127], v[126:127], v[142:143]
	v_pk_mul_f32 v[124:125], v[124:125], v[120:121]
	v_pk_mul_f32 v[126:127], v[126:127], v[122:123]
	v_pk_mul_f32 v[116:117], v[116:117], v[150:151] op_sel_hi:[1,0]
	v_pk_mul_f32 v[112:113], v[112:113], v[150:151] op_sel_hi:[1,0]
	v_pk_mul_f32 v[118:119], v[118:119], v[150:151] op_sel_hi:[1,0]
	v_pk_mul_f32 v[114:115], v[114:115], v[150:151] op_sel_hi:[1,0]
	v_pk_mul_f32 v[140:141], v[116:117], s[2:3] op_sel_hi:[1,0]
	v_pk_mul_f32 v[142:143], v[118:119], s[2:3] op_sel_hi:[1,0]
	v_exp_f32_e32 v140, v140
	v_exp_f32_e32 v141, v141
	v_exp_f32_e32 v142, v142
	v_exp_f32_e32 v143, v143
	v_pk_add_f32 v[140:141], v[140:141], 1.0 op_sel_hi:[1,0]
	v_pk_add_f32 v[142:143], v[142:143], 1.0 op_sel_hi:[1,0]
	v_rcp_f32_e32 v140, v140
	v_rcp_f32_e32 v141, v141
	v_rcp_f32_e32 v142, v142
	v_rcp_f32_e32 v143, v143
	v_pk_mul_f32 v[116:117], v[116:117], v[140:141]
	v_pk_mul_f32 v[118:119], v[118:119], v[142:143]
	v_pk_mul_f32 v[116:117], v[116:117], v[112:113]
	v_pk_mul_f32 v[118:119], v[118:119], v[114:115]
	v_cvt_pk_bf16_f32 v124, v124, v125
	v_cvt_pk_bf16_f32 v125, v126, v127
	v_cvt_pk_bf16_f32 v126, v116, v117
	v_cvt_pk_bf16_f32 v127, v118, v119
	global_store_dwordx4 v171, v[124:127], s[10:11]
	v_pk_mul_f32 v[108:109], v[108:109], v[152:153] op_sel_hi:[1,0]
	v_pk_mul_f32 v[104:105], v[104:105], v[152:153] op_sel_hi:[1,0]
	v_pk_mul_f32 v[110:111], v[110:111], v[152:153] op_sel_hi:[1,0]
	v_pk_mul_f32 v[106:107], v[106:107], v[152:153] op_sel_hi:[1,0]
	v_pk_mul_f32 v[140:141], v[108:109], s[2:3] op_sel_hi:[1,0]
	v_pk_mul_f32 v[142:143], v[110:111], s[2:3] op_sel_hi:[1,0]
	v_exp_f32_e32 v140, v140
	v_exp_f32_e32 v141, v141
	v_exp_f32_e32 v142, v142
	v_exp_f32_e32 v143, v143
	v_pk_add_f32 v[140:141], v[140:141], 1.0 op_sel_hi:[1,0]
	v_pk_add_f32 v[142:143], v[142:143], 1.0 op_sel_hi:[1,0]
	v_rcp_f32_e32 v140, v140
	v_rcp_f32_e32 v141, v141
	v_rcp_f32_e32 v142, v142
	v_rcp_f32_e32 v143, v143
	v_pk_mul_f32 v[108:109], v[108:109], v[140:141]
	v_pk_mul_f32 v[110:111], v[110:111], v[142:143]
	v_pk_mul_f32 v[108:109], v[108:109], v[104:105]
	v_pk_mul_f32 v[110:111], v[110:111], v[106:107]
	v_pk_mul_f32 v[100:101], v[100:101], v[152:153] op_sel_hi:[1,0]
	v_pk_mul_f32 v[96:97], v[96:97], v[152:153] op_sel_hi:[1,0]
	v_pk_mul_f32 v[102:103], v[102:103], v[152:153] op_sel_hi:[1,0]
	v_pk_mul_f32 v[98:99], v[98:99], v[152:153] op_sel_hi:[1,0]
	v_pk_mul_f32 v[140:141], v[100:101], s[2:3] op_sel_hi:[1,0]
	v_pk_mul_f32 v[142:143], v[102:103], s[2:3] op_sel_hi:[1,0]
	v_exp_f32_e32 v140, v140
	v_exp_f32_e32 v141, v141
	v_exp_f32_e32 v142, v142
	v_exp_f32_e32 v143, v143
	v_pk_add_f32 v[140:141], v[140:141], 1.0 op_sel_hi:[1,0]
	v_pk_add_f32 v[142:143], v[142:143], 1.0 op_sel_hi:[1,0]
	v_rcp_f32_e32 v140, v140
	v_rcp_f32_e32 v141, v141
	v_rcp_f32_e32 v142, v142
	v_rcp_f32_e32 v143, v143
	v_pk_mul_f32 v[100:101], v[100:101], v[140:141]
	v_pk_mul_f32 v[102:103], v[102:103], v[142:143]
	v_pk_mul_f32 v[100:101], v[100:101], v[96:97]
	v_pk_mul_f32 v[102:103], v[102:103], v[98:99]
	v_cvt_pk_bf16_f32 v108, v108, v109
	v_cvt_pk_bf16_f32 v109, v110, v111
	v_cvt_pk_bf16_f32 v110, v100, v101
	v_cvt_pk_bf16_f32 v111, v102, v103
	v_add_u32_e32 v149, 0x16000, v171
	global_store_dwordx4 v149, v[108:111], s[10:11]
	v_pk_mul_f32 v[92:93], v[92:93], v[154:155] op_sel_hi:[1,0]
	v_pk_mul_f32 v[88:89], v[88:89], v[154:155] op_sel_hi:[1,0]
	v_pk_mul_f32 v[94:95], v[94:95], v[154:155] op_sel_hi:[1,0]
	v_pk_mul_f32 v[90:91], v[90:91], v[154:155] op_sel_hi:[1,0]
	v_pk_mul_f32 v[140:141], v[92:93], s[2:3] op_sel_hi:[1,0]
	v_pk_mul_f32 v[142:143], v[94:95], s[2:3] op_sel_hi:[1,0]
; __device__ __forceinline__ unsigned pk2(float lo, float hi) { unsigned r; asm("v_cvt_pk_bf16_f32 %0, %1, %2" : "=v"(r) : "v"(lo), "v"(hi)); return r; }
; __device__ __forceinline__ float silu_f(float x) { return x * sigmoid_f(x); }
;     __device__ __forceinline__ void operator()(const f32x4 (&acc)[2][2][4][2], const pg8::Unit& u, int wr, int wc, int fr, int fq) const {
;     ...
;         for (int ai = 0; ai < 2; ++ai)
; #pragma unroll
;             for (int m = 0; m < 4; ++m) {
;                 const int r = row0 + ai * 128 + m * 16;
;                 const float rstd = __builtin_amdgcn_rsqf(rs[ai][m] * (1.0f / D) + EPS);
;                 float o[8];
; #pragma unroll
;                 for (int n = 0; n < 2; ++n)
; #pragma unroll
;                     for (int e = 0; e < 4; ++e) { const float g = acc[ai][0][m][n][e] * rstd, up = acc[ai][1][m][n][e] * rstd; o[4 * n + e] = silu_f(g) * up; }
;                 u32x4 w; w.x = pk2(o[0], o[1]); w.y = pk2(o[2], o[3]); w.z = pk2(o[4], o[5]); w.w = pk2(o[6], o[7]);
;                 *(u32x4*)(ACT + (size_t)r * FF + col0) = w;
	v_exp_f32_e32 v140, v140
	v_exp_f32_e32 v141, v141
	v_exp_f32_e32 v142, v142
	v_exp_f32_e32 v143, v143
	v_pk_add_f32 v[140:141], v[140:141], 1.0 op_sel_hi:[1,0]
	v_pk_add_f32 v[142:143], v[142:143], 1.0 op_sel_hi:[1,0]
	v_rcp_f32_e32 v140, v140
	v_rcp_f32_e32 v141, v141
	v_rcp_f32_e32 v142, v142
	v_rcp_f32_e32 v143, v143
	v_pk_mul_f32 v[92:93], v[92:93], v[140:141]
	v_pk_mul_f32 v[94:95], v[94:95], v[142:143]
	v_pk_mul_f32 v[92:93], v[92:93], v[88:89]
	v_pk_mul_f32 v[94:95], v[94:95], v[90:91]
	v_pk_mul_f32 v[84:85], v[84:85], v[154:155] op_sel_hi:[1,0]
	v_pk_mul_f32 v[80:81], v[80:81], v[154:155] op_sel_hi:[1,0]
	v_pk_mul_f32 v[86:87], v[86:87], v[154:155] op_sel_hi:[1,0]
	v_pk_mul_f32 v[82:83], v[82:83], v[154:155] op_sel_hi:[1,0]
	v_pk_mul_f32 v[140:141], v[84:85], s[2:3] op_sel_hi:[1,0]
	v_pk_mul_f32 v[142:143], v[86:87], s[2:3] op_sel_hi:[1,0]
	v_exp_f32_e32 v140, v140
	v_exp_f32_e32 v141, v141
	v_exp_f32_e32 v142, v142
	v_exp_f32_e32 v143, v143
	v_pk_add_f32 v[140:141], v[140:141], 1.0 op_sel_hi:[1,0]
	v_pk_add_f32 v[142:143], v[142:143], 1.0 op_sel_hi:[1,0]
	v_rcp_f32_e32 v140, v140
	v_rcp_f32_e32 v141, v141
	v_rcp_f32_e32 v142, v142
	v_rcp_f32_e32 v143, v143
	v_pk_mul_f32 v[84:85], v[84:85], v[140:141]
	v_pk_mul_f32 v[86:87], v[86:87], v[142:143]
	v_pk_mul_f32 v[84:85], v[84:85], v[80:81]
	v_pk_mul_f32 v[86:87], v[86:87], v[82:83]
	v_cvt_pk_bf16_f32 v92, v92, v93
	v_cvt_pk_bf16_f32 v93, v94, v95
	v_cvt_pk_bf16_f32 v94, v84, v85
	v_cvt_pk_bf16_f32 v95, v86, v87
	v_add_u32_e32 v149, 0x2c000, v171
	global_store_dwordx4 v149, v[92:95], s[10:11]
	v_pk_mul_f32 v[76:77], v[76:77], v[156:157] op_sel_hi:[1,0]
	v_pk_mul_f32 v[72:73], v[72:73], v[156:157] op_sel_hi:[1,0]
	v_pk_mul_f32 v[78:79], v[78:79], v[156:157] op_sel_hi:[1,0]
	v_pk_mul_f32 v[74:75], v[74:75], v[156:157] op_sel_hi:[1,0]
	v_pk_mul_f32 v[140:141], v[76:77], s[2:3] op_sel_hi:[1,0]
	v_pk_mul_f32 v[142:143], v[78:79], s[2:3] op_sel_hi:[1,0]
	v_exp_f32_e32 v140, v140
	v_exp_f32_e32 v141, v141
	v_exp_f32_e32 v142, v142
	v_exp_f32_e32 v143, v143
	v_pk_add_f32 v[140:141], v[140:141], 1.0 op_sel_hi:[1,0]
	v_pk_add_f32 v[142:143], v[142:143], 1.0 op_sel_hi:[1,0]
	v_rcp_f32_e32 v140, v140
	v_rcp_f32_e32 v141, v141
	v_rcp_f32_e32 v142, v142
	v_rcp_f32_e32 v143, v143
	v_pk_mul_f32 v[76:77], v[76:77], v[140:141]
	v_pk_mul_f32 v[78:79], v[78:79], v[142:143]
	v_pk_mul_f32 v[76:77], v[76:77], v[72:73]
	v_pk_mul_f32 v[78:79], v[78:79], v[74:75]
	v_pk_mul_f32 v[68:69], v[68:69], v[156:157] op_sel_hi:[1,0]
	v_pk_mul_f32 v[64:65], v[64:65], v[156:157] op_sel_hi:[1,0]
	v_pk_mul_f32 v[70:71], v[70:71], v[156:157] op_sel_hi:[1,0]
	v_pk_mul_f32 v[66:67], v[66:67], v[156:157] op_sel_hi:[1,0]
	v_pk_mul_f32 v[140:141], v[68:69], s[2:3] op_sel_hi:[1,0]
	v_pk_mul_f32 v[142:143], v[70:71], s[2:3] op_sel_hi:[1,0]
	v_exp_f32_e32 v140, v140
	v_exp_f32_e32 v141, v141
	v_exp_f32_e32 v142, v142
	v_exp_f32_e32 v143, v143
	v_pk_add_f32 v[140:141], v[140:141], 1.0 op_sel_hi:[1,0]
	v_pk_add_f32 v[142:143], v[142:143], 1.0 op_sel_hi:[1,0]
	v_rcp_f32_e32 v140, v140
	v_rcp_f32_e32 v141, v141
	v_rcp_f32_e32 v142, v142
	v_rcp_f32_e32 v143, v143
	v_pk_mul_f32 v[68:69], v[68:69], v[140:141]
	v_pk_mul_f32 v[70:71], v[70:71], v[142:143]
	v_pk_mul_f32 v[68:69], v[68:69], v[64:65]
	v_pk_mul_f32 v[70:71], v[70:71], v[66:67]
	v_cvt_pk_bf16_f32 v76, v76, v77
	v_cvt_pk_bf16_f32 v77, v78, v79
	v_cvt_pk_bf16_f32 v78, v68, v69
	v_cvt_pk_bf16_f32 v79, v70, v71
	v_add_u32_e32 v149, 0x42000, v171
	global_store_dwordx4 v149, v[76:79], s[10:11]
	v_pk_mul_f32 v[60:61], v[60:61], v[158:159] op_sel_hi:[1,0]
	v_pk_mul_f32 v[56:57], v[56:57], v[158:159] op_sel_hi:[1,0]
	v_pk_mul_f32 v[62:63], v[62:63], v[158:159] op_sel_hi:[1,0]
	v_pk_mul_f32 v[58:59], v[58:59], v[158:159] op_sel_hi:[1,0]
	v_pk_mul_f32 v[140:141], v[60:61], s[2:3] op_sel_hi:[1,0]
	v_pk_mul_f32 v[142:143], v[62:63], s[2:3] op_sel_hi:[1,0]
	v_exp_f32_e32 v140, v140
	v_exp_f32_e32 v141, v141
	v_exp_f32_e32 v142, v142
	v_exp_f32_e32 v143, v143
	v_pk_add_f32 v[140:141], v[140:141], 1.0 op_sel_hi:[1,0]
	v_pk_add_f32 v[142:143], v[142:143], 1.0 op_sel_hi:[1,0]
	v_rcp_f32_e32 v140, v140
	v_rcp_f32_e32 v141, v141
	v_rcp_f32_e32 v142, v142
	v_rcp_f32_e32 v143, v143
	v_pk_mul_f32 v[60:61], v[60:61], v[140:141]
	v_pk_mul_f32 v[62:63], v[62:63], v[142:143]
	v_pk_mul_f32 v[60:61], v[60:61], v[56:57]
	v_pk_mul_f32 v[62:63], v[62:63], v[58:59]
	v_pk_mul_f32 v[52:53], v[52:53], v[158:159] op_sel_hi:[1,0]
	v_pk_mul_f32 v[48:49], v[48:49], v[158:159] op_sel_hi:[1,0]
	v_pk_mul_f32 v[54:55], v[54:55], v[158:159] op_sel_hi:[1,0]
	v_pk_mul_f32 v[50:51], v[50:51], v[158:159] op_sel_hi:[1,0]
	v_pk_mul_f32 v[140:141], v[52:53], s[2:3] op_sel_hi:[1,0]
	v_pk_mul_f32 v[142:143], v[54:55], s[2:3] op_sel_hi:[1,0]
	v_exp_f32_e32 v140, v140
	v_exp_f32_e32 v141, v141
	v_exp_f32_e32 v142, v142
	v_exp_f32_e32 v143, v143
	v_pk_add_f32 v[140:141], v[140:141], 1.0 op_sel_hi:[1,0]
	v_pk_add_f32 v[142:143], v[142:143], 1.0 op_sel_hi:[1,0]
	v_rcp_f32_e32 v140, v140
	v_rcp_f32_e32 v141, v141
	v_rcp_f32_e32 v142, v142
	v_rcp_f32_e32 v143, v143
	v_pk_mul_f32 v[52:53], v[52:53], v[140:141]
	v_pk_mul_f32 v[54:55], v[54:55], v[142:143]
	v_pk_mul_f32 v[52:53], v[52:53], v[48:49]
	v_pk_mul_f32 v[54:55], v[54:55], v[50:51]
	v_cvt_pk_bf16_f32 v60, v60, v61
	v_cvt_pk_bf16_f32 v61, v62, v63
	v_cvt_pk_bf16_f32 v62, v52, v53
	v_cvt_pk_bf16_f32 v63, v54, v55
	v_add_u32_e32 v149, 0xb0000, v171
	global_store_dwordx4 v149, v[60:63], s[10:11]
	v_pk_mul_f32 v[44:45], v[44:45], v[160:161] op_sel_hi:[1,0]
	v_pk_mul_f32 v[40:41], v[40:41], v[160:161] op_sel_hi:[1,0]
	v_pk_mul_f32 v[46:47], v[46:47], v[160:161] op_sel_hi:[1,0]
; __device__ __forceinline__ unsigned pk2(float lo, float hi) { unsigned r; asm("v_cvt_pk_bf16_f32 %0, %1, %2" : "=v"(r) : "v"(lo), "v"(hi)); return r; }
; __device__ __forceinline__ float silu_f(float x) { return x * sigmoid_f(x); }
;     __device__ __forceinline__ void operator()(const f32x4 (&acc)[2][2][4][2], const pg8::Unit& u, int wr, int wc, int fr, int fq) const {
;     ...
;         for (int ai = 0; ai < 2; ++ai)
; #pragma unroll
;             for (int m = 0; m < 4; ++m) {
;                 const int r = row0 + ai * 128 + m * 16;
;                 const float rstd = __builtin_amdgcn_rsqf(rs[ai][m] * (1.0f / D) + EPS);
;                 float o[8];
; #pragma unroll
;                 for (int n = 0; n < 2; ++n)
; #pragma unroll
;                     for (int e = 0; e < 4; ++e) { const float g = acc[ai][0][m][n][e] * rstd, up = acc[ai][1][m][n][e] * rstd; o[4 * n + e] = silu_f(g) * up; }
;                 u32x4 w; w.x = pk2(o[0], o[1]); w.y = pk2(o[2], o[3]); w.z = pk2(o[4], o[5]); w.w = pk2(o[6], o[7]);
;                 *(u32x4*)(ACT + (size_t)r * FF + col0) = w;
;             }
	v_pk_mul_f32 v[42:43], v[42:43], v[160:161] op_sel_hi:[1,0]
	v_pk_mul_f32 v[140:141], v[44:45], s[2:3] op_sel_hi:[1,0]
	v_pk_mul_f32 v[142:143], v[46:47], s[2:3] op_sel_hi:[1,0]
	v_exp_f32_e32 v140, v140
	v_exp_f32_e32 v141, v141
	v_exp_f32_e32 v142, v142
	v_exp_f32_e32 v143, v143
	v_pk_add_f32 v[140:141], v[140:141], 1.0 op_sel_hi:[1,0]
	v_pk_add_f32 v[142:143], v[142:143], 1.0 op_sel_hi:[1,0]
	v_rcp_f32_e32 v140, v140
	v_rcp_f32_e32 v141, v141
	v_rcp_f32_e32 v142, v142
	v_rcp_f32_e32 v143, v143
	v_pk_mul_f32 v[44:45], v[44:45], v[140:141]
	v_pk_mul_f32 v[46:47], v[46:47], v[142:143]
	v_pk_mul_f32 v[44:45], v[44:45], v[40:41]
	v_pk_mul_f32 v[46:47], v[46:47], v[42:43]
	v_pk_mul_f32 v[36:37], v[36:37], v[160:161] op_sel_hi:[1,0]
	v_pk_mul_f32 v[32:33], v[32:33], v[160:161] op_sel_hi:[1,0]
	v_pk_mul_f32 v[38:39], v[38:39], v[160:161] op_sel_hi:[1,0]
	v_pk_mul_f32 v[34:35], v[34:35], v[160:161] op_sel_hi:[1,0]
	v_pk_mul_f32 v[140:141], v[36:37], s[2:3] op_sel_hi:[1,0]
	v_pk_mul_f32 v[142:143], v[38:39], s[2:3] op_sel_hi:[1,0]
	v_exp_f32_e32 v140, v140
	v_exp_f32_e32 v141, v141
	v_exp_f32_e32 v142, v142
	v_exp_f32_e32 v143, v143
	v_pk_add_f32 v[140:141], v[140:141], 1.0 op_sel_hi:[1,0]
	v_pk_add_f32 v[142:143], v[142:143], 1.0 op_sel_hi:[1,0]
	v_rcp_f32_e32 v140, v140
	v_rcp_f32_e32 v141, v141
	v_rcp_f32_e32 v142, v142
	v_rcp_f32_e32 v143, v143
	v_pk_mul_f32 v[36:37], v[36:37], v[140:141]
	v_pk_mul_f32 v[38:39], v[38:39], v[142:143]
	v_pk_mul_f32 v[36:37], v[36:37], v[32:33]
	v_pk_mul_f32 v[38:39], v[38:39], v[34:35]
	v_cvt_pk_bf16_f32 v44, v44, v45
	v_cvt_pk_bf16_f32 v45, v46, v47
	v_cvt_pk_bf16_f32 v46, v36, v37
	v_cvt_pk_bf16_f32 v47, v38, v39
	v_add_u32_e32 v149, 0xc6000, v171
	global_store_dwordx4 v149, v[44:47], s[10:11]
	v_pk_mul_f32 v[28:29], v[28:29], v[144:145] op_sel_hi:[1,0]
	v_pk_mul_f32 v[24:25], v[24:25], v[144:145] op_sel_hi:[1,0]
	v_pk_mul_f32 v[30:31], v[30:31], v[144:145] op_sel_hi:[1,0]
	v_pk_mul_f32 v[26:27], v[26:27], v[144:145] op_sel_hi:[1,0]
	v_pk_mul_f32 v[140:141], v[28:29], s[2:3] op_sel_hi:[1,0]
	v_pk_mul_f32 v[142:143], v[30:31], s[2:3] op_sel_hi:[1,0]
	v_exp_f32_e32 v140, v140
	v_exp_f32_e32 v141, v141
	v_exp_f32_e32 v142, v142
	v_exp_f32_e32 v143, v143
	v_pk_add_f32 v[140:141], v[140:141], 1.0 op_sel_hi:[1,0]
	v_pk_add_f32 v[142:143], v[142:143], 1.0 op_sel_hi:[1,0]
	v_rcp_f32_e32 v140, v140
	v_rcp_f32_e32 v141, v141
	v_rcp_f32_e32 v142, v142
	v_rcp_f32_e32 v143, v143
	v_pk_mul_f32 v[28:29], v[28:29], v[140:141]
	v_pk_mul_f32 v[30:31], v[30:31], v[142:143]
	v_pk_mul_f32 v[28:29], v[28:29], v[24:25]
	v_pk_mul_f32 v[30:31], v[30:31], v[26:27]
	v_pk_mul_f32 v[20:21], v[20:21], v[144:145] op_sel_hi:[1,0]
	v_pk_mul_f32 v[16:17], v[16:17], v[144:145] op_sel_hi:[1,0]
	v_pk_mul_f32 v[22:23], v[22:23], v[144:145] op_sel_hi:[1,0]
	v_pk_mul_f32 v[18:19], v[18:19], v[144:145] op_sel_hi:[1,0]
	v_pk_mul_f32 v[140:141], v[20:21], s[2:3] op_sel_hi:[1,0]
	v_pk_mul_f32 v[142:143], v[22:23], s[2:3] op_sel_hi:[1,0]
	v_exp_f32_e32 v140, v140
	v_exp_f32_e32 v141, v141
	v_exp_f32_e32 v142, v142
	v_exp_f32_e32 v143, v143
	v_pk_add_f32 v[140:141], v[140:141], 1.0 op_sel_hi:[1,0]
	v_pk_add_f32 v[142:143], v[142:143], 1.0 op_sel_hi:[1,0]
	v_rcp_f32_e32 v140, v140
	v_rcp_f32_e32 v141, v141
	v_rcp_f32_e32 v142, v142
	v_rcp_f32_e32 v143, v143
	v_pk_mul_f32 v[20:21], v[20:21], v[140:141]
	v_pk_mul_f32 v[22:23], v[22:23], v[142:143]
	v_pk_mul_f32 v[20:21], v[20:21], v[16:17]
	v_pk_mul_f32 v[22:23], v[22:23], v[18:19]
	v_cvt_pk_bf16_f32 v28, v28, v29
	v_cvt_pk_bf16_f32 v29, v30, v31
	v_cvt_pk_bf16_f32 v30, v20, v21
	v_cvt_pk_bf16_f32 v31, v22, v23
	v_add_u32_e32 v149, 0xdc000, v171
	global_store_dwordx4 v149, v[28:31], s[10:11]
	v_pk_mul_f32 v[12:13], v[12:13], v[174:175] op_sel_hi:[1,0]
	v_pk_mul_f32 v[8:9], v[8:9], v[174:175] op_sel_hi:[1,0]
	v_pk_mul_f32 v[14:15], v[14:15], v[174:175] op_sel_hi:[1,0]
	v_pk_mul_f32 v[10:11], v[10:11], v[174:175] op_sel_hi:[1,0]
	v_pk_mul_f32 v[140:141], v[12:13], s[2:3] op_sel_hi:[1,0]
	v_pk_mul_f32 v[142:143], v[14:15], s[2:3] op_sel_hi:[1,0]
	v_exp_f32_e32 v140, v140
	v_exp_f32_e32 v141, v141
	v_exp_f32_e32 v142, v142
	v_exp_f32_e32 v143, v143
	v_pk_add_f32 v[140:141], v[140:141], 1.0 op_sel_hi:[1,0]
	v_pk_add_f32 v[142:143], v[142:143], 1.0 op_sel_hi:[1,0]
	v_rcp_f32_e32 v140, v140
	v_rcp_f32_e32 v141, v141
	v_rcp_f32_e32 v142, v142
	v_rcp_f32_e32 v143, v143
	v_pk_mul_f32 v[12:13], v[12:13], v[140:141]
	v_pk_mul_f32 v[14:15], v[14:15], v[142:143]
	v_pk_mul_f32 v[12:13], v[12:13], v[8:9]
	v_pk_mul_f32 v[14:15], v[14:15], v[10:11]
	v_pk_mul_f32 v[4:5], v[4:5], v[174:175] op_sel_hi:[1,0]
	v_pk_mul_f32 v[0:1], v[0:1], v[174:175] op_sel_hi:[1,0]
	v_pk_mul_f32 v[6:7], v[6:7], v[174:175] op_sel_hi:[1,0]
	v_pk_mul_f32 v[2:3], v[2:3], v[174:175] op_sel_hi:[1,0]
	v_pk_mul_f32 v[140:141], v[4:5], s[2:3] op_sel_hi:[1,0]
	v_pk_mul_f32 v[142:143], v[6:7], s[2:3] op_sel_hi:[1,0]
	v_exp_f32_e32 v140, v140
	v_exp_f32_e32 v141, v141
	v_exp_f32_e32 v142, v142
	v_exp_f32_e32 v143, v143
	v_pk_add_f32 v[140:141], v[140:141], 1.0 op_sel_hi:[1,0]
	v_pk_add_f32 v[142:143], v[142:143], 1.0 op_sel_hi:[1,0]
	v_rcp_f32_e32 v140, v140
	v_rcp_f32_e32 v141, v141
	v_rcp_f32_e32 v142, v142
	v_rcp_f32_e32 v143, v143
	v_pk_mul_f32 v[4:5], v[4:5], v[140:141]
	v_pk_mul_f32 v[6:7], v[6:7], v[142:143]
	v_pk_mul_f32 v[4:5], v[4:5], v[0:1]
	v_pk_mul_f32 v[6:7], v[6:7], v[2:3]
	v_cvt_pk_bf16_f32 v12, v12, v13
	v_cvt_pk_bf16_f32 v13, v14, v15
	v_cvt_pk_bf16_f32 v14, v4, v5
	v_cvt_pk_bf16_f32 v15, v6, v7
	v_add_u32_e32 v149, 0xf2000, v171
	global_store_dwordx4 v149, v[12:15], s[10:11]
	s_mov_b64 s[2:3], -1
	s_andn2_b64 vcc, exec, s[6:7]
	s_cbranch_vccnz .LBB0_515
	s_andn2_b64 vcc, exec, s[8:9]
	s_cbranch_vccnz .LBB0_514
	s_barrier
	s_branch .LBB0_514
